# attention: hand-scheduled copy of the chunk loop for units with a previous key block (K frags double-buffered, next block's bias+K LDS reads issued before current block's QK MFMAs, exp/sum in the LDS-
# baseline (speedup 1.0000x reference)
; #define LAS __attribute__((address_space(3)))
; __device__ __forceinline__ void attn_phase(int wave_s, LAS unsigned char* lds, const bf16* QKV, bf16* O, const float* qg, const float* kg, const float* sinks, const float* bt) {
;     ...
;         for (int i = 0; i < 4; ++i) { int tq = tid; asm volatile("" : "+v"(tq)); const int p = tq + NTHR * i, jrow = p >> 3, ch = p & 7; const bool ok = (nb > 0) || (jrow >= 128);
;             v4u kw = (v4u){0u, 0u, 0u, 0u}, vw = (v4u){0u, 0u, 0u, 0u};
;             if (ok) { const bf16* src = QKV + (size_t)(rowbase + jrow) * NQKV + NH * HD + kvh * HD + ch * 8; kw = *(const v4u*)src; vw = *(const v4u*)(src + NKV * HD); }
;             float kf[8] = {bflo(kw.x), bfhi(kw.x), bflo(kw.y), bfhi(kw.y), bflo(kw.z), bfhi(kw.z), bflo(kw.w), bfhi(kw.w)};
;             float s = 0.f;
; #pragma unroll
;             for (int e = 0; e < 8; ++e) s += kf[e] * kf[e];
;             s = sum8(s);
;             const float rs = __builtin_amdgcn_rsqf(s * (1.0f / 64.0f) + EPS);
;             const f32x4 g0 = *(const f32x4*)(kg + ch * 8), g1 = *(const f32x4*)(kg + ch * 8 + 4);
;             v4u ko; ko.x = pk2(kf[0] * rs * g0.x, kf[1] * rs * g0.y); ko.y = pk2(kf[2] * rs * g0.z, kf[3] * rs * g0.w); ko.z = pk2(kf[4] * rs * g1.x, kf[5] * rs * g1.y); ko.w = pk2(kf[6] * rs * g1.z, kf[7] * rs * g1.w);
;             *(LAS v4u*)(Ks + jrow * KS_STRIDE + ch * 8) = ko;
;             LAS bf16* vd = Vt + (ch * 8) * VT_STRIDE + jrow;
;             vd[0 * VT_STRIDE] = (bf16)(vw.x & 0xffffu); vd[1 * VT_STRIDE] = (bf16)(vw.x >> 16); vd[2 * VT_STRIDE] = (bf16)(vw.y & 0xffffu); vd[3 * VT_STRIDE] = (bf16)(vw.y >> 16);
;             vd[4 * VT_STRIDE] = (bf16)(vw.z & 0xffffu); vd[5 * VT_STRIDE] = (bf16)(vw.z >> 16); vd[6 * VT_STRIDE] = (bf16)(vw.w & 0xffffu); vd[7 * VT_STRIDE] = (bf16)(vw.w >> 16); }
;         for (int e = tid; e < 8 * 192; e += NTHR) { const int hh = e / 192, dist = e % 192 - 32; Bs[e] = (dist >= 0 && dist < 128) ? bt[(kvh * 8 + hh) * 128 + dist] - shift * LOG2E : -1e30f; }
;         __syncthreads();
;         const int h = kvh * 8 + wid; const float sink2 = (sinks[h] - shift) * LOG2E;
;         const LAS float* Bh = Bs + wid * 192 + (r32 - 4 * hi);
;         LAS float* wsf = (LAS float*)(lds + ALDS_END) + wid * 32;
;         const bf16* Qb = QKV + ((size_t)b * SEQ + nb * 128 + r32) * NQKV + h * HD + hi * 8;
;         v4u qw[4];
; #pragma unroll
.LBB0_492:
	s_or_b64 exec, exec, s[2:3]
	v_lshl_add_u64 v[10:11], v[14:15], 2, s[28:29]
	global_load_dwordx4 v[16:19], v[10:11], off
	global_load_dwordx4 v[20:23], v[10:11], off offset:16
	s_waitcnt vmcnt(3)
	v_lshlrev_b32_e32 v26, 16, v6
	v_and_b32_e32 v27, 0xffff0000, v6
	v_lshlrev_b32_e32 v10, 16, v9
	v_and_b32_e32 v11, 0xffff0000, v9
	v_lshlrev_b32_e32 v24, 16, v8
	v_and_b32_e32 v25, 0xffff0000, v8
	v_lshlrev_b32_e32 v8, 16, v7
	v_and_b32_e32 v9, 0xffff0000, v7
	v_pk_mul_f32 v[30:31], v[26:27], v[26:27]
	v_pk_mul_f32 v[28:29], v[8:9], v[8:9]
	v_add_f32_e32 v30, v30, v31
	v_add_f32_e32 v28, v28, v30
	v_lshlrev_b32_e32 v32, 1, v14
	v_pk_mul_f32 v[14:15], v[24:25], v[24:25]
	v_add_f32_e32 v28, v29, v28
	v_add_f32_e32 v14, v14, v28
	v_pk_mul_f32 v[6:7], v[10:11], v[10:11]
	v_add_f32_e32 v14, v15, v14
	v_add_f32_e32 v6, v6, v14
	v_add_f32_e32 v6, v7, v6
	v_mul_lo_u32 v13, v12, s67
	v_mul_u32_u24_e32 v1, 0x1040, v1
	v_add_f32_dpp v6, v6, v6 quad_perm:[1,0,3,2] row_mask:0xf bank_mask:0xf bound_ctrl:1
	v_lshlrev_b32_e32 v7, 1, v12
	v_add3_u32 v28, 0, v13, v32
	v_add_f32_dpp v6, v6, v6 quad_perm:[2,3,0,1] row_mask:0xf bank_mask:0xf bound_ctrl:1
	v_add3_u32 v1, 0, v1, v7
	s_and_b32 s36, s34, 3
	v_add_f32_dpp v6, v6, v6 row_half_mirror row_mask:0xf bank_mask:0xf bound_ctrl:1
	v_fmamk_f32 v6, v6, 0x3c800000, v250
	v_rsq_f32_e32 v6, v6
	s_nop 0
	v_pk_mul_f32 v[12:13], v[6:7], v[26:27] op_sel_hi:[0,1]
	v_pk_mul_f32 v[8:9], v[6:7], v[8:9] op_sel_hi:[0,1]
	v_pk_mul_f32 v[14:15], v[6:7], v[24:25] op_sel_hi:[0,1]
	v_pk_mul_f32 v[6:7], v[6:7], v[10:11] op_sel_hi:[0,1]
	s_waitcnt vmcnt(1)
	v_pk_mul_f32 v[10:11], v[16:17], v[12:13]
	v_pk_mul_f32 v[8:9], v[18:19], v[8:9]
	s_waitcnt vmcnt(0)
	v_pk_mul_f32 v[12:13], v[20:21], v[14:15]
	v_pk_mul_f32 v[14:15], v[22:23], v[6:7]
	v_cvt_pk_bf16_f32 v6, v10, v11
	v_cvt_pk_bf16_f32 v7, v8, v9
	v_cvt_pk_bf16_f32 v8, v12, v13
	v_cvt_pk_bf16_f32 v9, v14, v15
	ds_write_b128 v28, v[6:9]
	ds_write_b16 v1, v2 offset:36864
	ds_write_b16_d16_hi v1, v2 offset:37384
	ds_write_b16 v1, v3 offset:37904
	ds_write_b16_d16_hi v1, v3 offset:38424
	ds_write_b16 v1, v4 offset:38944
	ds_write_b16_d16_hi v1, v4 offset:39464
	ds_write_b16 v1, v5 offset:39984
	ds_write_b16_d16_hi v1, v5 offset:40504
	s_and_saveexec_b64 s[2:3], s[14:15]
	s_cbranch_execz .LBB0_497
	s_lshl_b32 s10, s36, 10
	s_sub_i32 s37, s10, 32
	s_mov_b32 s12, 0x2aaaaaab
	s_movk_i32 s13, 0xff40
	s_movk_i32 s40, 0xffe0
	s_add_i32 s10, 0, 0x11200
	v_lshl_add_u32 v1, v142, 2, s10
	v_add_u32_e32 v9, 0x200, v142
	v_add_u32_e32 v10, 0x400, v142
	v_mul_hi_i32 v11, v142, s12
	v_mul_hi_i32 v12, v9, s12
	v_mul_hi_i32 v13, v10, s12
	v_lshrrev_b32_e32 v14, 31, v11
	v_lshrrev_b32_e32 v15, 31, v12
	v_lshrrev_b32_e32 v16, 31, v13
	v_ashrrev_i32_e32 v11, 5, v11
	v_ashrrev_i32_e32 v12, 5, v12
	v_ashrrev_i32_e32 v13, 5, v13
	v_add_u32_e32 v11, v11, v14
	v_add_u32_e32 v12, v12, v15
	v_add_u32_e32 v13, v13, v16
	v_mul_lo_u32 v14, v11, s13
	v_mul_lo_u32 v15, v12, s13
	v_mul_lo_u32 v16, v13, s13
	v_add3_u32 v14, v142, v14, s40
	v_add3_u32 v15, v9, v15, s40
	v_add3_u32 v16, v10, v16, s40
	v_add_u32_e32 v18, s37, v142
	v_add_u32_e32 v20, s37, v9
	v_add_u32_e32 v22, s37, v10
	v_lshlrev_b32_e32 v11, 6, v11
	v_lshlrev_b32_e32 v12, 6, v12
	v_lshlrev_b32_e32 v13, 6, v13
	v_sub_u32_e32 v18, v18, v11
	v_sub_u32_e32 v20, v20, v12
	v_sub_u32_e32 v22, v22, v13
	v_ashrrev_i32_e32 v19, 31, v18
	v_ashrrev_i32_e32 v21, 31, v20
	v_ashrrev_i32_e32 v23, 31, v22
	v_lshl_add_u64 v[18:19], v[18:19], 2, s[20:21]
	v_lshl_add_u64 v[20:21], v[20:21], 2, s[20:21]
	v_lshl_add_u64 v[22:23], v[22:23], 2, s[20:21]
	v_cmp_gt_u32_e64 s[10:11], s66, v14
	v_cmp_gt_u32_e64 s[12:13], s66, v15
	v_cmp_gt_u32_e64 s[40:41], s66, v16
	v_mov_b32_e32 v27, 0xf149f2ca
	s_mov_b64 s[84:85], exec
	s_and_b64 exec, s[84:85], s[10:11]
	global_load_dword v24, v[18:19], off
	s_and_b64 exec, s[84:85], s[12:13]
	global_load_dword v25, v[20:21], off
	s_and_b64 exec, s[84:85], s[40:41]
	global_load_dword v26, v[22:23], off
	s_mov_b64 exec, s[84:85]
	s_waitcnt vmcnt(0)
	v_sub_f32_e32 v24, v24, v144
	v_sub_f32_e32 v25, v25, v144
	v_sub_f32_e32 v26, v26, v144
	v_cndmask_b32_e64 v24, v27, v24, s[10:11]
	v_cndmask_b32_e64 v25, v27, v25, s[12:13]
	v_cndmask_b32_e64 v26, v27, v26, s[40:41]
	ds_write_b32 v1, v24
	ds_write_b32 v1, v25 offset:2048
	ds_write_b32 v1, v26 offset:4096
.LBB0_497:
	s_or_b64 exec, exec, s[2:3]
	s_lshr_b32 s2, s35, 2
	s_and_b32 s10, s2, 63
	s_lshl_b32 s37, s10, 7
	s_lshl_b32 s2, s36, 9
	s_lshl_b32 s36, s10, 19
	s_lshl_b32 s10, s31, 3
	s_add_i32 s2, s23, s2
	s_add_i32 s10, s10, s16
	s_ashr_i32 s3, s2, 31
	s_ashr_i32 s11, s10, 31
	s_lshl_b64 s[2:3], s[2:3], 1
	s_lshl_b64 s[12:13], s[10:11], 2
	s_add_u32 s12, s17, s12
	s_addc_u32 s13, s22, s13
	s_lshl_b32 s11, s30, 7
	s_or_b32 s11, s8, s11
	v_or_b32_e32 v4, s11, v128
	v_mov_b64_e32 v[2:3], s[26:27]
	s_waitcnt lgkmcnt(0)
	s_barrier
	global_load_dword v1, v0, s[12:13]
	v_mad_u64_u32 v[2:3], s[12:13], v4, s70, v[2:3]
	v_mov_b32_e32 v4, 0x1400
	s_lshl_b32 s10, s10, 6
	v_mad_i32_i24 v3, s9, v4, v3
	s_ashr_i32 s11, s10, 31
	v_lshl_add_u64 v[2:3], s[10:11], 1, v[2:3]
	v_mov_b32_e32 v137, v0
	v_lshl_add_u64 v[2:3], v[2:3], 0, v[136:137]
	global_load_dwordx4 v[96:99], v[2:3], off
	global_load_dwordx4 v[100:103], v[2:3], off offset:32
	global_load_dwordx4 v[104:107], v[2:3], off offset:64
	global_load_dwordx4 v[108:111], v[2:3], off offset:96
	s_add_u32 s8, s37, s8
	s_addc_u32 s9, 0, s9
	s_lshl_b64 s[6:7], s[6:7], 25
	v_mov_b64_e32 v[2:3], s[2:3]
	v_lshl_add_u64 v[4:5], s[8:9], 0, v[128:129]
	s_or_b32 s6, s6, s36
	v_mad_u64_u32 v[2:3], s[8:9], v4, s70, v[2:3]
	s_add_u32 s2, s6, s2
	v_mad_i32_i24 v3, v5, s70, v3
	s_addc_u32 s3, s7, s3
	v_lshl_add_u64 v[138:139], v[132:133], 0, v[2:3]
	v_lshl_add_u64 v[140:141], v[134:135], 0, s[2:3]
	s_mov_b32 s36, 0
	s_mov_b64 s[90:91], 0
	v_mov_b32_e32 v156, v151
	v_mov_b32_e32 v157, v150
	s_waitcnt vmcnt(4)
	v_sub_f32_e32 v1, v1, v143
	v_mul_f32_e32 v1, 0x3fb8aa3b, v1
	v_exp_f32_e32 v137, v1
	s_waitcnt vmcnt(0)
	s_and_b64 vcc, exec, s[88:89]
	s_cbranch_vccnz .Lfa_top
	s_branch .LBB0_499

; __device__ __forceinline__ float sum_x32(float t) { float a = t, b = t; asm volatile("s_nop 1\n\tv_permlane32_swap_b32 %0, %1" : "+v"(a), "+v"(b)); return a + b; }
; #define LAS __attribute__((address_space(3)))
; __device__ __forceinline__ unsigned pk2(float lo, float hi) { f32x2_t v = {lo, hi}; bf16x2_t b = __builtin_convertvector(v, bf16x2_t); return __builtin_bit_cast(unsigned, b); }
; __device__ __forceinline__ void attn_phase(int wave_s, LAS unsigned char* lds, const bf16* QKV, bf16* O, const float* qg, const float* kg, const float* sinks, const float* bt) {
;     ...
;             { float s = 0.f;
; #pragma unroll
;                 for (int d0 = 0; d0 < 4; ++d0) {
;                     const float f0 = bflo(qw[d0].x), f1 = bfhi(qw[d0].x), f2 = bflo(qw[d0].y), f3 = bfhi(qw[d0].y), f4 = bflo(qw[d0].z), f5 = bfhi(qw[d0].z), f6 = bflo(qw[d0].w), f7 = bfhi(qw[d0].w);
;                     s += (f0 * f0 + f1 * f1) + (f2 * f2 + f3 * f3) + (f4 * f4 + f5 * f5) + (f6 * f6 + f7 * f7); }
;                 s = sum_x32(s);
;                 const float rs = __builtin_amdgcn_rsqf(s * (1.0f / 64.0f) + EPS) * (0.125f * LOG2E);
; #pragma unroll
;                 for (int d0 = 0; d0 < 4; ++d0) { const f32x4 g0 = *(const f32x4*)(qg + d0 * 16 + hi * 8), g1 = *(const f32x4*)(qg + d0 * 16 + hi * 8 + 4);
;                     v4u o; o.x = pk2(bflo(qw[d0].x) * rs * g0.x, bfhi(qw[d0].x) * rs * g0.y); o.y = pk2(bflo(qw[d0].y) * rs * g0.z, bfhi(qw[d0].y) * rs * g0.w);
;                     o.z = pk2(bflo(qw[d0].z) * rs * g1.x, bfhi(qw[d0].z) * rs * g1.y); o.w = pk2(bflo(qw[d0].w) * rs * g1.z, bfhi(qw[d0].w) * rs * g1.w);
;                     qr[d0] = __builtin_bit_cast(bf16x8, o); } }
;             if (c < 3) {
; #pragma unroll
;                 for (int d0 = 0; d0 < 4; ++d0) qw[d0] = *(const v4u*)(Qb + (size_t)(32 * (c + 1)) * NQKV + d0 * 16); }
;             f32x16 p[5]; float l = 0.f;
; #pragma unroll
;             for (int kk = 0; kk < 5; ++kk) { const bool blk_ok = (nb > 0) || (c + kk >= 4);
;                 if (blk_ok) {
; #pragma unroll
;                     for (int r = 0; r < 16; ++r) p[kk][r] = Bh[160 - 32 * kk - (r & 3) - 8 * (r >> 2)];
; #pragma unroll
;                     for (int d0 = 0; d0 < 4; ++d0) { const bf16x8 kf = *(const LAS bf16x8*)(Ks + ((c + kk) * 32 + r32) * KS_STRIDE + d0 * 16 + hi * 8);
.Lfa_top:
	ds_read2_b32 v[80:81], v145 offset0:32 offset1:31
	ds_read2_b32 v[82:83], v145 offset0:30 offset1:29
	ds_read2_b32 v[84:85], v145 offset0:24 offset1:23
	ds_read2_b32 v[86:87], v145 offset0:22 offset1:21
	ds_read2_b32 v[88:89], v145 offset0:16 offset1:15
	ds_read2_b32 v[90:91], v145 offset0:14 offset1:13
	ds_read2_b32 v[92:93], v145 offset0:8 offset1:7
	ds_read2_b32 v[94:95], v145 offset0:6 offset1:5
	ds_read_b128 v[212:215], v157 offset:18432
	ds_read_b128 v[216:219], v157 offset:18464
	ds_read_b128 v[220:223], v157 offset:18496
	ds_read_b128 v[224:227], v157 offset:18528
	v_add_u32_e32 v244, 0x4000, v156
	v_and_b32_e32 v53, 0xffff0000, v103
	v_and_b32_e32 v55, 0xffff0000, v102
	v_mov_b32_e32 v54, v53
	v_and_b32_e32 v67, 0xffff0000, v100
	v_pk_mul_f32 v[10:11], v[54:55], v[54:55]
	v_lshlrev_b32_e32 v54, 16, v101
	v_and_b32_e32 v65, 0xffff0000, v101
	v_mov_b32_e32 v64, v67
	v_lshlrev_b32_e32 v52, 16, v102
	v_lshlrev_b32_e32 v56, 16, v100
	v_mov_b32_e32 v57, v54
	v_pk_mul_f32 v[12:13], v[64:65], v[64:65]
	v_lshlrev_b32_e32 v46, 16, v105
	v_lshlrev_b32_e32 v50, 16, v103
	v_mov_b32_e32 v51, v52
	v_pk_fma_f32 v[12:13], v[56:57], v[56:57], v[12:13]
	v_and_b32_e32 v77, 0xffff0000, v96
	v_and_b32_e32 v47, 0xffff0000, v105
	v_mul_f32_e32 v6, v46, v46
	v_pk_fma_f32 v[10:11], v[50:51], v[50:51], v[10:11]
	v_pk_add_f32 v[12:13], v[12:13], v[12:13] op_sel:[0,1] op_sel_hi:[1,0]
	v_and_b32_e32 v71, 0xffff0000, v99
	v_lshlrev_b32_e32 v66, 16, v97
	v_and_b32_e32 v75, 0xffff0000, v97
	v_mov_b32_e32 v74, v77
	v_pk_fma_f32 v[6:7], v[46:47], v[46:47], v[6:7] op_sel_hi:[1,1,0]
	v_lshlrev_b32_e32 v48, 16, v104
	v_pk_add_f32 v[12:13], v[10:11], v[12:13] op_sel:[1,0] op_sel_hi:[0,1]
	v_lshlrev_b32_e32 v64, 16, v98
	v_and_b32_e32 v69, 0xffff0000, v98
	v_mov_b32_e32 v68, v71
	v_lshlrev_b32_e32 v72, 16, v96
	v_mov_b32_e32 v73, v66
	v_pk_mul_f32 v[14:15], v[74:75], v[74:75]
	v_lshlrev_b32_e32 v38, 16, v109
	v_and_b32_e32 v39, 0xffff0000, v109
	v_and_b32_e32 v43, 0xffff0000, v108
	v_and_b32_e32 v49, 0xffff0000, v104
	v_mul_f32_e32 v6, v48, v48
	v_pk_add_f32 v[10:11], v[10:11], v[12:13]
	v_lshlrev_b32_e32 v62, 16, v99
	v_mov_b32_e32 v63, v64
	v_pk_mul_f32 v[12:13], v[68:69], v[68:69]
	v_pk_fma_f32 v[14:15], v[72:73], v[72:73], v[14:15]
	v_and_b32_e32 v1, 0xffff0000, v110
	v_pk_mul_f32 v[4:5], v[38:39], v[38:39]
	v_lshlrev_b32_e32 v44, 16, v106
	v_and_b32_e32 v61, 0xffff0000, v106
	v_pk_fma_f32 v[8:9], v[48:49], v[48:49], v[6:7] op_sel_hi:[1,1,0]
	v_pk_fma_f32 v[12:13], v[62:63], v[62:63], v[12:13]
	v_pk_add_f32 v[14:15], v[14:15], v[14:15] op_sel:[0,1] op_sel_hi:[1,0]
	v_mov_b32_e32 v60, v43
	v_lshlrev_b32_e32 v34, 16, v111
	v_and_b32_e32 v35, 0xffff0000, v111
	v_lshlrev_b32_e32 v40, 16, v108
	v_lshlrev_b32_e32 v42, 16, v107
	v_and_b32_e32 v59, 0xffff0000, v107
	v_pk_add_f32 v[14:15], v[12:13], v[14:15] op_sel:[1,0] op_sel_hi:[0,1]
	v_mov_b32_e32 v58, v1
	v_mov_b32_e32 v41, v44
	v_pk_mul_f32 v[16:17], v[60:61], v[60:61]
	v_mov_b32_e32 v8, v4
	v_mov_b32_e32 v6, v5
	v_pk_mul_f32 v[2:3], v[34:35], v[34:35]
	v_lshlrev_b32_e32 v36, 16, v110
	v_pk_add_f32 v[12:13], v[12:13], v[14:15]
	v_mov_b32_e32 v37, v42
	v_pk_mul_f32 v[14:15], v[58:59], v[58:59]
	v_pk_fma_f32 v[16:17], v[40:41], v[40:41], v[16:17]
	v_pk_add_f32 v[4:5], v[8:9], v[6:7]
	v_pk_fma_f32 v[14:15], v[36:37], v[36:37], v[14:15]
	v_pk_add_f32 v[4:5], v[16:17], v[4:5]
	v_mov_b32_e32 v6, v2
	v_mov_b32_e32 v7, v10
	v_pk_mov_b32 v[2:3], v[2:3], v[12:13] op_sel:[1,0]
	v_pk_add_f32 v[4:5], v[14:15], v[4:5]
	v_pk_add_f32 v[2:3], v[6:7], v[2:3]
	s_cmp_eq_u32 s90, 0x60000
	v_pk_add_f32 v[2:3], v[4:5], v[2:3]
	s_nop 0
	v_add_f32_e32 v58, v2, v3
	v_mov_b32_e32 v60, v58
	s_nop 1
	v_permlane32_swap_b32 v58, v60
	s_cbranch_scc1 .Lfa_q
	global_load_dwordx4 v[96:99], v[138:139], off offset:-64
	global_load_dwordx4 v[100:103], v[138:139], off offset:-32
	global_load_dwordx4 v[104:107], v[138:139], off
	global_load_dwordx4 v[108:111], v[138:139], off offset:32
.Lfa_q:
	v_mov_b32_e32 v37, v1
	v_add_f32_e32 v1, v58, v60
	v_fmamk_f32 v1, v1, 0x3c800000, v250
	v_rsq_f32_e32 v1, v1
	v_mov_b32_e32 v73, v77
	v_mov_b32_e32 v45, v61
	v_mov_b32_e32 v57, v67
	v_mul_f32_e32 v58, 0x3e38aa3b, v1
	v_pk_mul_f32 v[60:61], v[58:59], v[72:73] op_sel_hi:[0,1]
	v_mov_b32_e32 v67, v75
	v_pk_mul_f32 v[30:31], v[168:169], v[60:61]
	v_mov_b32_e32 v51, v53
	v_cvt_pk_bf16_f32 v112, v30, v31
	v_pk_mul_f32 v[30:31], v[58:59], v[66:67] op_sel_hi:[0,1]
	v_mov_b32_e32 v53, v55
	v_mov_b32_e32 v55, v65
	v_mov_b32_e32 v65, v69
	v_pk_mul_f32 v[30:31], v[170:171], v[30:31]
	v_mov_b32_e32 v63, v71
	v_cvt_pk_bf16_f32 v113, v30, v31
	v_pk_mul_f32 v[30:31], v[58:59], v[64:65] op_sel_hi:[0,1]
	v_pk_mul_f32 v[26:27], v[164:165], v[30:31]
	v_mov_b32_e32 v41, v43
	v_cvt_pk_bf16_f32 v114, v26, v27
	v_pk_mul_f32 v[26:27], v[58:59], v[62:63] op_sel_hi:[0,1]
	v_pk_mul_f32 v[26:27], v[166:167], v[26:27]
	v_mov_b32_e32 v43, v59
	v_cvt_pk_bf16_f32 v115, v26, v27
	v_pk_mul_f32 v[26:27], v[58:59], v[56:57] op_sel_hi:[0,1]
	v_pk_mul_f32 v[22:23], v[176:177], v[26:27]
	v_cndmask_b32_e64 v1, 0, 1, s[88:89]
	v_cvt_pk_bf16_f32 v116, v22, v23
	v_pk_mul_f32 v[22:23], v[58:59], v[54:55] op_sel_hi:[0,1]
	v_pk_mul_f32 v[22:23], v[178:179], v[22:23]
	v_cmp_ne_u32_e64 s[6:7], 1, v1
	v_cvt_pk_bf16_f32 v117, v22, v23
	v_pk_mul_f32 v[22:23], v[58:59], v[52:53] op_sel_hi:[0,1]
	v_pk_mul_f32 v[18:19], v[172:173], v[22:23]
	s_andn2_b64 vcc, exec, s[88:89]
	v_cvt_pk_bf16_f32 v118, v18, v19
	v_pk_mul_f32 v[18:19], v[58:59], v[50:51] op_sel_hi:[0,1]
	v_pk_mul_f32 v[18:19], v[174:175], v[18:19]
	s_nop 0
	v_cvt_pk_bf16_f32 v119, v18, v19
	v_pk_mul_f32 v[18:19], v[58:59], v[48:49] op_sel_hi:[0,1]
	v_pk_mul_f32 v[14:15], v[184:185], v[18:19]
	s_nop 0
	v_cvt_pk_bf16_f32 v120, v14, v15
	v_pk_mul_f32 v[14:15], v[58:59], v[46:47] op_sel_hi:[0,1]
	v_pk_mul_f32 v[14:15], v[186:187], v[14:15]
	s_nop 0
	v_cvt_pk_bf16_f32 v121, v14, v15
	v_pk_mul_f32 v[14:15], v[58:59], v[44:45] op_sel_hi:[0,1]
	v_pk_mul_f32 v[10:11], v[180:181], v[14:15]
	s_nop 0
	v_cvt_pk_bf16_f32 v122, v10, v11
	v_pk_mul_f32 v[10:11], v[58:59], v[42:43] op_sel_hi:[0,1]
	v_pk_mul_f32 v[10:11], v[182:183], v[10:11]
	s_nop 0
	v_cvt_pk_bf16_f32 v123, v10, v11
	v_pk_mul_f32 v[10:11], v[58:59], v[40:41] op_sel_hi:[0,1]
	v_pk_mul_f32 v[6:7], v[10:11], v[192:193]
	s_nop 0
	v_cvt_pk_bf16_f32 v124, v6, v7
	v_pk_mul_f32 v[6:7], v[58:59], v[38:39] op_sel_hi:[0,1]
	v_pk_mul_f32 v[6:7], v[6:7], v[194:195]
	s_nop 0
	v_cvt_pk_bf16_f32 v125, v6, v7
	v_pk_mul_f32 v[6:7], v[58:59], v[36:37] op_sel_hi:[0,1]
	v_pk_mul_f32 v[2:3], v[6:7], v[188:189]
	s_nop 0
	v_cvt_pk_bf16_f32 v126, v2, v3
	v_pk_mul_f32 v[2:3], v[58:59], v[34:35] op_sel_hi:[0,1]
	v_pk_mul_f32 v[2:3], v[2:3], v[190:191]
	s_nop 0
	v_cvt_pk_bf16_f32 v127, v2, v3
	s_waitcnt lgkmcnt(0)
; #define LAS __attribute__((address_space(3)))
; __device__ __forceinline__ void attn_phase(int wave_s, LAS unsigned char* lds, const bf16* QKV, bf16* O, const float* qg, const float* kg, const float* sinks, const float* bt) {
;     ...
;             f32x16 p[5]; float l = 0.f;
; #pragma unroll
;             for (int kk = 0; kk < 5; ++kk) { const bool blk_ok = (nb > 0) || (c + kk >= 4);
;                 if (blk_ok) {
; #pragma unroll
;                     for (int r = 0; r < 16; ++r) p[kk][r] = Bh[160 - 32 * kk - (r & 3) - 8 * (r >> 2)];
; #pragma unroll
;                     for (int d0 = 0; d0 < 4; ++d0) { const bf16x8 kf = *(const LAS bf16x8*)(Ks + ((c + kk) * 32 + r32) * KS_STRIDE + d0 * 16 + hi * 8);
;                         p[kk] = __builtin_amdgcn_mfma_f32_32x32x16_bf16(kf, qr[d0], p[kk], 0, 0, 0); }
;                 } else p[kk] = (f32x16){}; }
; #pragma unroll
;             for (int kk = 0; kk < 5; ++kk) { const bool blk_ok = (nb > 0) || (c + kk >= 4);
;                 if (blk_ok) {
; #pragma unroll
;                     for (int r = 0; r < 16; ++r) { const float e = __builtin_amdgcn_exp2f(p[kk][r]); p[kk][r] = e; l += e; } } }
	ds_read2_b32 v[16:17], v145 offset0:160 offset1:159
	ds_read2_b32 v[18:19], v145 offset0:158 offset1:157
	ds_read2_b32 v[20:21], v145 offset0:152 offset1:151
	ds_read2_b32 v[22:23], v145 offset0:150 offset1:149
	ds_read2_b32 v[24:25], v145 offset0:144 offset1:143
	ds_read2_b32 v[26:27], v145 offset0:142 offset1:141
	ds_read2_b32 v[28:29], v145 offset0:136 offset1:135
	ds_read2_b32 v[30:31], v145 offset0:134 offset1:133
	ds_read_b128 v[196:199], v157
	ds_read_b128 v[200:203], v157 offset:32
	ds_read_b128 v[204:207], v157 offset:64
	ds_read_b128 v[208:211], v157 offset:96
	v_mfma_f32_32x32x16_bf16 v[80:95], v[212:215], v[112:115], v[80:95]
	v_mfma_f32_32x32x16_bf16 v[80:95], v[216:219], v[116:119], v[80:95]
	v_mfma_f32_32x32x16_bf16 v[80:95], v[220:223], v[120:123], v[80:95]
	v_mfma_f32_32x32x16_bf16 v[80:95], v[224:227], v[124:127], v[80:95]
	s_waitcnt lgkmcnt(0)
	ds_read2_b32 v[32:33], v145 offset0:128 offset1:127
	ds_read2_b32 v[34:35], v145 offset0:126 offset1:125
	ds_read2_b32 v[36:37], v145 offset0:120 offset1:119
	ds_read2_b32 v[38:39], v145 offset0:118 offset1:117
	ds_read2_b32 v[40:41], v145 offset0:112 offset1:111
	ds_read2_b32 v[42:43], v145 offset0:110 offset1:109
	ds_read2_b32 v[44:45], v145 offset0:104 offset1:103
	ds_read2_b32 v[46:47], v145 offset0:102 offset1:101
	ds_read_b128 v[212:215], v157 offset:4608
	ds_read_b128 v[216:219], v157 offset:4640
	ds_read_b128 v[220:223], v157 offset:4672
	ds_read_b128 v[224:227], v157 offset:4704
	v_mfma_f32_32x32x16_bf16 v[16:31], v[196:199], v[112:115], v[16:31]
	v_mfma_f32_32x32x16_bf16 v[16:31], v[200:203], v[116:119], v[16:31]
	v_mfma_f32_32x32x16_bf16 v[16:31], v[204:207], v[120:123], v[16:31]
	v_mfma_f32_32x32x16_bf16 v[16:31], v[208:211], v[124:127], v[16:31]
	v_exp_f32_e32 v80, v80
	v_exp_f32_e32 v81, v81
	v_exp_f32_e32 v82, v82
	v_exp_f32_e32 v83, v83
	v_add_f32_e32 v1, 0, v80
	v_exp_f32_e32 v84, v84
	v_add_f32_e32 v1, v81, v1
	v_exp_f32_e32 v85, v85
	v_add_f32_e32 v1, v82, v1
	v_exp_f32_e32 v86, v86
	v_add_f32_e32 v1, v83, v1
	v_exp_f32_e32 v87, v87
	v_add_f32_e32 v1, v84, v1
	v_exp_f32_e32 v88, v88
	v_add_f32_e32 v1, v85, v1
	v_exp_f32_e32 v89, v89
	v_add_f32_e32 v1, v86, v1
	v_exp_f32_e32 v90, v90
	v_add_f32_e32 v1, v87, v1
	v_exp_f32_e32 v91, v91
	v_add_f32_e32 v1, v88, v1
	v_exp_f32_e32 v92, v92
	v_add_f32_e32 v1, v89, v1
	v_exp_f32_e32 v93, v93
	v_add_f32_e32 v1, v90, v1
	v_exp_f32_e32 v94, v94
	v_add_f32_e32 v1, v91, v1
	v_exp_f32_e32 v95, v95
	v_add_f32_e32 v1, v92, v1
	v_add_f32_e32 v1, v93, v1
	v_add_f32_e32 v1, v94, v1
	v_add_f32_e32 v1, v95, v1
	s_waitcnt lgkmcnt(0)
	ds_read2_b32 v[48:49], v145 offset0:96 offset1:95
	ds_read2_b32 v[50:51], v145 offset0:94 offset1:93
	ds_read2_b32 v[52:53], v145 offset0:88 offset1:87
	ds_read2_b32 v[54:55], v145 offset0:86 offset1:85
	ds_read2_b32 v[56:57], v145 offset0:80 offset1:79
	ds_read2_b32 v[58:59], v145 offset0:78 offset1:77
	ds_read2_b32 v[60:61], v145 offset0:72 offset1:71
	ds_read2_b32 v[62:63], v145 offset0:70 offset1:69
	ds_read_b128 v[196:199], v157 offset:9216
	ds_read_b128 v[200:203], v157 offset:9248
	ds_read_b128 v[204:207], v157 offset:9280
	ds_read_b128 v[208:211], v157 offset:9312
	v_mfma_f32_32x32x16_bf16 v[32:47], v[212:215], v[112:115], v[32:47]
	v_mfma_f32_32x32x16_bf16 v[32:47], v[216:219], v[116:119], v[32:47]
	v_mfma_f32_32x32x16_bf16 v[32:47], v[220:223], v[120:123], v[32:47]
	v_mfma_f32_32x32x16_bf16 v[32:47], v[224:227], v[124:127], v[32:47]
	v_exp_f32_e32 v16, v16
	v_exp_f32_e32 v17, v17
	v_exp_f32_e32 v18, v18
	v_exp_f32_e32 v19, v19
	v_add_f32_e32 v1, v16, v1
	v_exp_f32_e32 v20, v20
	v_add_f32_e32 v1, v17, v1
	v_exp_f32_e32 v21, v21
	v_add_f32_e32 v1, v18, v1
	v_exp_f32_e32 v22, v22
	v_add_f32_e32 v1, v19, v1
	v_exp_f32_e32 v23, v23
	v_add_f32_e32 v1, v20, v1
	v_exp_f32_e32 v24, v24
	v_add_f32_e32 v1, v21, v1
	v_exp_f32_e32 v25, v25
	v_add_f32_e32 v1, v22, v1
	v_exp_f32_e32 v26, v26
	v_add_f32_e32 v1, v23, v1
	v_exp_f32_e32 v27, v27
	v_add_f32_e32 v1, v24, v1
	v_exp_f32_e32 v28, v28
	v_add_f32_e32 v1, v25, v1
	v_exp_f32_e32 v29, v29
	v_add_f32_e32 v1, v26, v1
	v_exp_f32_e32 v30, v30
	v_add_f32_e32 v1, v27, v1
	v_exp_f32_e32 v31, v31
	v_add_f32_e32 v1, v28, v1
	v_add_f32_e32 v1, v29, v1
	v_add_f32_e32 v1, v30, v1
	v_add_f32_e32 v1, v31, v1
	s_waitcnt lgkmcnt(0)
	ds_read2_b32 v[64:65], v145 offset0:64 offset1:63
	ds_read2_b32 v[66:67], v145 offset0:62 offset1:61
	ds_read2_b32 v[68:69], v145 offset0:56 offset1:55
	ds_read2_b32 v[70:71], v145 offset0:54 offset1:53
	ds_read2_b32 v[72:73], v145 offset0:48 offset1:47
	ds_read2_b32 v[74:75], v145 offset0:46 offset1:45
	ds_read2_b32 v[76:77], v145 offset0:40 offset1:39
	ds_read2_b32 v[78:79], v145 offset0:38 offset1:37
	ds_read_b128 v[212:215], v157 offset:13824
	ds_read_b128 v[216:219], v157 offset:13856
	ds_read_b128 v[220:223], v157 offset:13888
	ds_read_b128 v[224:227], v157 offset:13920
	v_mfma_f32_32x32x16_bf16 v[48:63], v[196:199], v[112:115], v[48:63]
	v_mfma_f32_32x32x16_bf16 v[48:63], v[200:203], v[116:119], v[48:63]
	v_mfma_f32_32x32x16_bf16 v[48:63], v[204:207], v[120:123], v[48:63]
	v_mfma_f32_32x32x16_bf16 v[48:63], v[208:211], v[124:127], v[48:63]
	v_exp_f32_e32 v32, v32
	v_exp_f32_e32 v33, v33
	v_exp_f32_e32 v34, v34
	v_exp_f32_e32 v35, v35
	v_add_f32_e32 v1, v32, v1
	v_exp_f32_e32 v36, v36
	v_add_f32_e32 v1, v33, v1
	v_exp_f32_e32 v37, v37
	v_add_f32_e32 v1, v34, v1
	v_exp_f32_e32 v38, v38
	v_add_f32_e32 v1, v35, v1
	v_exp_f32_e32 v39, v39
	v_add_f32_e32 v1, v36, v1
	v_exp_f32_e32 v40, v40
	v_add_f32_e32 v1, v37, v1
	v_exp_f32_e32 v41, v41
	v_add_f32_e32 v1, v38, v1
	v_exp_f32_e32 v42, v42
	v_add_f32_e32 v1, v39, v1
	v_exp_f32_e32 v43, v43
	v_add_f32_e32 v1, v40, v1
	v_exp_f32_e32 v44, v44
	v_add_f32_e32 v1, v41, v1
	v_exp_f32_e32 v45, v45
	v_add_f32_e32 v1, v42, v1
	v_exp_f32_e32 v46, v46
	v_add_f32_e32 v1, v43, v1
	v_exp_f32_e32 v47, v47
	v_add_f32_e32 v1, v44, v1
	v_add_f32_e32 v1, v45, v1
	v_add_f32_e32 v1, v46, v1
	v_add_f32_e32 v1, v47, v1
	s_waitcnt lgkmcnt(0)
; __device__ __forceinline__ float sum_x32(float t) { float a = t, b = t; asm volatile("s_nop 1\n\tv_permlane32_swap_b32 %0, %1" : "+v"(a), "+v"(b)); return a + b; }
; #define LAS __attribute__((address_space(3)))
; __device__ __forceinline__ unsigned pk2(float lo, float hi) { f32x2_t v = {lo, hi}; bf16x2_t b = __builtin_convertvector(v, bf16x2_t); return __builtin_bit_cast(unsigned, b); }
; __device__ __forceinline__ void attn_phase(int wave_s, LAS unsigned char* lds, const bf16* QKV, bf16* O, const float* qg, const float* kg, const float* sinks, const float* bt) {
;     ...
; #pragma unroll
;             for (int kk = 0; kk < 5; ++kk) { const bool blk_ok = (nb > 0) || (c + kk >= 4);
;                 if (blk_ok) {
; #pragma unroll
;                     for (int r = 0; r < 16; ++r) { const float e = __builtin_amdgcn_exp2f(p[kk][r]); p[kk][r] = e; l += e; } } }
;             l = sum_x32(l); l += __builtin_amdgcn_exp2f(sink2);
;             if (hi == 0) wsf[r32] = __builtin_amdgcn_rcpf(l);
;             f32x16 o[2]; o[0] = (f32x16){}; o[1] = (f32x16){};
; #pragma unroll
;             for (int kk = 0; kk < 5; ++kk) { const bool blk_ok = (nb > 0) || (c + kk >= 4);
;                 if (blk_ok) {
; #pragma unroll
;                     for (int ks = 0; ks < 2; ++ks) { v4u pw; pw.x = pk2(p[kk][8 * ks + 0], p[kk][8 * ks + 1]); pw.y = pk2(p[kk][8 * ks + 2], p[kk][8 * ks + 3]);
;                         pw.z = pk2(p[kk][8 * ks + 4], p[kk][8 * ks + 5]); pw.w = pk2(p[kk][8 * ks + 6], p[kk][8 * ks + 7]);
;                         const bf16x8 pa = __builtin_bit_cast(bf16x8, pw);
; #pragma unroll
;                         for (int db = 0; db < 2; ++db) { const LAS bf16* vp = Vt + (db * 32 + r32) * VT_STRIDE + 32 * (c + kk) + 16 * ks + 4 * hi;
;                             const v2u lo = *(const LAS v2u*)vp, hh = *(const LAS v2u*)(vp + 8); const v4u vv = (v4u){lo.x, lo.y, hh.x, hh.y};
;                             o[db] = __builtin_amdgcn_mfma_f32_32x32x16_bf16(pa, __builtin_bit_cast(bf16x8, vv), o[db], 0, 0, 0); } } } }
	ds_read2_b64 v[196:199], v156 offset1:2
	ds_read2_b64 v[200:203], v244 offset0:32 offset1:34
	ds_read2_b64 v[204:207], v156 offset0:4 offset1:6
	ds_read2_b64 v[208:211], v244 offset0:36 offset1:38
	v_mfma_f32_32x32x16_bf16 v[64:79], v[212:215], v[112:115], v[64:79]
	v_mfma_f32_32x32x16_bf16 v[64:79], v[216:219], v[116:119], v[64:79]
	v_mfma_f32_32x32x16_bf16 v[64:79], v[220:223], v[120:123], v[64:79]
	v_mfma_f32_32x32x16_bf16 v[64:79], v[224:227], v[124:127], v[64:79]
	ds_read2_b64 v[212:215], v156 offset0:8 offset1:10
	ds_read2_b64 v[216:219], v244 offset0:40 offset1:42
	ds_read2_b64 v[220:223], v156 offset0:12 offset1:14
	ds_read2_b64 v[224:227], v244 offset0:44 offset1:46
	v_exp_f32_e32 v48, v48
	v_exp_f32_e32 v49, v49
	v_exp_f32_e32 v50, v50
	v_exp_f32_e32 v51, v51
	v_add_f32_e32 v1, v48, v1
	v_exp_f32_e32 v52, v52
	v_add_f32_e32 v1, v49, v1
	v_exp_f32_e32 v53, v53
	v_add_f32_e32 v1, v50, v1
	v_exp_f32_e32 v54, v54
	v_add_f32_e32 v1, v51, v1
	v_exp_f32_e32 v55, v55
	v_add_f32_e32 v1, v52, v1
	v_exp_f32_e32 v56, v56
	v_add_f32_e32 v1, v53, v1
	v_exp_f32_e32 v57, v57
	v_add_f32_e32 v1, v54, v1
	v_exp_f32_e32 v58, v58
	v_add_f32_e32 v1, v55, v1
	v_exp_f32_e32 v59, v59
	v_add_f32_e32 v1, v56, v1
	v_exp_f32_e32 v60, v60
	v_add_f32_e32 v1, v57, v1
	v_exp_f32_e32 v61, v61
	v_add_f32_e32 v1, v58, v1
	v_exp_f32_e32 v62, v62
	v_add_f32_e32 v1, v59, v1
	v_exp_f32_e32 v63, v63
	v_add_f32_e32 v1, v60, v1
	v_add_f32_e32 v1, v61, v1
	v_add_f32_e32 v1, v62, v1
	v_add_f32_e32 v1, v63, v1
	v_exp_f32_e32 v64, v64
	v_exp_f32_e32 v65, v65
	v_exp_f32_e32 v66, v66
	v_exp_f32_e32 v67, v67
	v_add_f32_e32 v1, v64, v1
	v_exp_f32_e32 v68, v68
	v_add_f32_e32 v1, v65, v1
	v_exp_f32_e32 v69, v69
	v_add_f32_e32 v1, v66, v1
	v_exp_f32_e32 v70, v70
	v_add_f32_e32 v1, v67, v1
	v_exp_f32_e32 v71, v71
	v_add_f32_e32 v1, v68, v1
	v_exp_f32_e32 v72, v72
	v_add_f32_e32 v1, v69, v1
	v_exp_f32_e32 v73, v73
	v_add_f32_e32 v1, v70, v1
	v_exp_f32_e32 v74, v74
	v_add_f32_e32 v1, v71, v1
	v_exp_f32_e32 v75, v75
	v_add_f32_e32 v1, v72, v1
	v_exp_f32_e32 v76, v76
	v_add_f32_e32 v1, v73, v1
	v_exp_f32_e32 v77, v77
	v_add_f32_e32 v1, v74, v1
	v_exp_f32_e32 v78, v78
	v_add_f32_e32 v1, v75, v1
	v_exp_f32_e32 v79, v79
	v_add_f32_e32 v1, v76, v1
	v_add_f32_e32 v1, v77, v1
	v_add_f32_e32 v1, v78, v1
	v_add_f32_e32 v1, v79, v1
	v_mov_b32_e32 v2, v1
	s_nop 1
	v_permlane32_swap_b32 v2, v1
	s_and_saveexec_b64 s[2:3], s[4:5]
	s_cbranch_execz .Lfa_nod
	v_add_f32_e32 v1, v2, v1
	v_add_f32_e32 v1, v137, v1
	v_rcp_f32_e32 v1, v1
	ds_write_b32 v146, v1
.Lfa_nod:
	s_or_b64 exec, exec, s[2:3]
	v_cvt_pk_bf16_f32 v112, v80, v81
	v_cvt_pk_bf16_f32 v113, v82, v83
	v_cvt_pk_bf16_f32 v114, v84, v85
	v_cvt_pk_bf16_f32 v115, v86, v87
	v_cvt_pk_bf16_f32 v116, v88, v89
	v_cvt_pk_bf16_f32 v117, v90, v91
	v_cvt_pk_bf16_f32 v118, v92, v93
	v_cvt_pk_bf16_f32 v119, v94, v95
	v_cvt_pk_bf16_f32 v228, v16, v17
	v_cvt_pk_bf16_f32 v229, v18, v19
	v_cvt_pk_bf16_f32 v230, v20, v21
	v_cvt_pk_bf16_f32 v231, v22, v23
	v_cvt_pk_bf16_f32 v240, v24, v25
	v_cvt_pk_bf16_f32 v241, v26, v27
	v_cvt_pk_bf16_f32 v242, v28, v29
	v_cvt_pk_bf16_f32 v243, v30, v31
	s_waitcnt lgkmcnt(4)
	v_mfma_f32_32x32x16_bf16 v[2:17], v[228:231], v[196:199], 0
	v_mfma_f32_32x32x16_bf16 v[80:95], v[228:231], v[200:203], 0
	v_mfma_f32_32x32x16_bf16 v[2:17], v[240:243], v[204:207], v[2:17]
	v_mfma_f32_32x32x16_bf16 v[80:95], v[240:243], v[208:211], v[80:95]
	ds_read2_b64 v[196:199], v156 offset0:16 offset1:18
	ds_read2_b64 v[200:203], v244 offset0:48 offset1:50
	ds_read2_b64 v[204:207], v156 offset0:20 offset1:22
	ds_read2_b64 v[208:211], v244 offset0:52 offset1:54
	v_cvt_pk_bf16_f32 v228, v32, v33
	v_cvt_pk_bf16_f32 v229, v34, v35
	v_cvt_pk_bf16_f32 v230, v36, v37
	v_cvt_pk_bf16_f32 v231, v38, v39
	v_cvt_pk_bf16_f32 v240, v40, v41
	v_cvt_pk_bf16_f32 v241, v42, v43
	v_cvt_pk_bf16_f32 v242, v44, v45
	v_cvt_pk_bf16_f32 v243, v46, v47
	s_waitcnt lgkmcnt(4)
	v_mfma_f32_32x32x16_bf16 v[2:17], v[228:231], v[212:215], v[2:17]
	v_mfma_f32_32x32x16_bf16 v[80:95], v[228:231], v[216:219], v[80:95]
	v_mfma_f32_32x32x16_bf16 v[2:17], v[240:243], v[220:223], v[2:17]
	v_mfma_f32_32x32x16_bf16 v[80:95], v[240:243], v[224:227], v[80:95]
	ds_read2_b64 v[212:215], v156 offset0:24 offset1:26
	ds_read2_b64 v[216:219], v244 offset0:56 offset1:58
	ds_read2_b64 v[220:223], v156 offset0:28 offset1:30
	ds_read2_b64 v[224:227], v244 offset0:60 offset1:62
	v_cvt_pk_bf16_f32 v228, v48, v49
	v_cvt_pk_bf16_f32 v229, v50, v51
	v_cvt_pk_bf16_f32 v230, v52, v53
	v_cvt_pk_bf16_f32 v231, v54, v55
	v_cvt_pk_bf16_f32 v240, v56, v57
	v_cvt_pk_bf16_f32 v241, v58, v59
	v_cvt_pk_bf16_f32 v242, v60, v61
	v_cvt_pk_bf16_f32 v243, v62, v63
	s_waitcnt lgkmcnt(4)
	v_mfma_f32_32x32x16_bf16 v[2:17], v[228:231], v[196:199], v[2:17]
	v_mfma_f32_32x32x16_bf16 v[80:95], v[228:231], v[200:203], v[80:95]
	v_mfma_f32_32x32x16_bf16 v[2:17], v[240:243], v[204:207], v[2:17]
	v_mfma_f32_32x32x16_bf16 v[80:95], v[240:243], v[208:211], v[80:95]
	ds_read2_b64 v[196:199], v156 offset0:32 offset1:34
	ds_read2_b64 v[200:203], v244 offset0:64 offset1:66
	ds_read2_b64 v[204:207], v156 offset0:36 offset1:38
	ds_read2_b64 v[208:211], v244 offset0:68 offset1:70
	v_cvt_pk_bf16_f32 v228, v64, v65
	v_cvt_pk_bf16_f32 v229, v66, v67
	v_cvt_pk_bf16_f32 v230, v68, v69
	v_cvt_pk_bf16_f32 v231, v70, v71
	v_cvt_pk_bf16_f32 v240, v72, v73
	v_cvt_pk_bf16_f32 v241, v74, v75
	v_cvt_pk_bf16_f32 v242, v76, v77
	v_cvt_pk_bf16_f32 v243, v78, v79
	s_waitcnt lgkmcnt(4)
; #define LAS __attribute__((address_space(3)))
; #define LDS_WAIT() asm volatile("s_waitcnt lgkmcnt(0)" ::: "memory")
; __device__ __forceinline__ unsigned pk2(float lo, float hi) { f32x2_t v = {lo, hi}; bf16x2_t b = __builtin_convertvector(v, bf16x2_t); return __builtin_bit_cast(unsigned, b); }
; __device__ __forceinline__ void attn_phase(int wave_s, LAS unsigned char* lds, const bf16* QKV, bf16* O, const float* qg, const float* kg, const float* sinks, const float* bt) {
;     ...
;                         for (int db = 0; db < 2; ++db) { const LAS bf16* vp = Vt + (db * 32 + r32) * VT_STRIDE + 32 * (c + kk) + 16 * ks + 4 * hi;
;                             const v2u lo = *(const LAS v2u*)vp, hh = *(const LAS v2u*)(vp + 8); const v4u vv = (v4u){lo.x, lo.y, hh.x, hh.y};
;                             o[db] = __builtin_amdgcn_mfma_f32_32x32x16_bf16(pa, __builtin_bit_cast(bf16x8, vv), o[db], 0, 0, 0); } } } }
;             LDS_WAIT();
;             LAS bf16* stg = (LAS bf16*)(lds + ALDS_OST) + wid * 2048;
; #pragma unroll
;             for (int rq = 0; rq < 4; ++rq) { const f32x4 iv = *(const LAS f32x4*)(wsf + 8 * rq + 4 * hi);
; #pragma unroll
;                 for (int e = 0; e < 4; ++e) { const int r = 4 * rq + e, q = 8 * rq + 4 * hi + e; stg[q * 64 + r32] = (bf16)(pk2(o[0][r] * iv[e], 0.f) & 0xffffu); stg[q * 64 + 32 + r32] = (bf16)(pk2(o[1][r] * iv[e], 0.f) & 0xffffu); } }
;             LDS_WAIT();
;             bf16* Ow = O + ((size_t)b * SEQ + nb * 128 + 32 * c) * DM + h * HD;
; #pragma unroll
;             for (int i = 0; i < 4; ++i) { const int row = i * 8 + (lane >> 3), ch = lane & 7; const v4u v = *(const LAS v4u*)(stg + row * 64 + ch * 8); *(v4u*)(Ow + (size_t)row * DM + ch * 8) = v; }
	v_mfma_f32_32x32x16_bf16 v[2:17], v[228:231], v[212:215], v[2:17]
	v_mfma_f32_32x32x16_bf16 v[80:95], v[228:231], v[216:219], v[80:95]
	v_mfma_f32_32x32x16_bf16 v[2:17], v[240:243], v[220:223], v[2:17]
	v_mfma_f32_32x32x16_bf16 v[80:95], v[240:243], v[224:227], v[80:95]
	s_waitcnt lgkmcnt(0)
	v_mfma_f32_32x32x16_bf16 v[2:17], v[112:115], v[196:199], v[2:17]
	v_mfma_f32_32x32x16_bf16 v[80:95], v[112:115], v[200:203], v[80:95]
	v_mfma_f32_32x32x16_bf16 v[2:17], v[116:119], v[204:207], v[2:17]
	v_mfma_f32_32x32x16_bf16 v[80:95], v[116:119], v[208:211], v[80:95]
	v_add_u32_e32 v157, 0x1200, v157
	v_add_u32_e32 v156, 64, v156
	s_mov_b32 s2, 0x1d400000
	ds_read_b128 v[18:21], v147
	s_waitcnt lgkmcnt(0)
	s_nop 7
	v_mul_f32_e32 v1, v2, v18
	v_cvt_pk_bf16_f32 v1, v1, s0
	ds_write_b16 v152, v1
	v_mul_f32_e32 v1, v80, v18
	v_cvt_pk_bf16_f32 v1, v1, s0
	ds_write_b16 v152, v1 offset:64
	v_mul_f32_e32 v1, v3, v19
	v_cvt_pk_bf16_f32 v1, v1, s0
	ds_write_b16 v152, v1 offset:128
	v_mul_f32_e32 v1, v81, v19
	v_cvt_pk_bf16_f32 v1, v1, s0
	ds_write_b16 v152, v1 offset:192
	v_mul_f32_e32 v1, v4, v20
	v_cvt_pk_bf16_f32 v1, v1, s0
	ds_write_b16 v152, v1 offset:256
	v_mul_f32_e32 v1, v82, v20
	v_cvt_pk_bf16_f32 v1, v1, s0
	ds_write_b16 v152, v1 offset:320
	v_mul_f32_e32 v1, v5, v21
	v_cvt_pk_bf16_f32 v1, v1, s0
	ds_write_b16 v152, v1 offset:384
	v_mul_f32_e32 v1, v83, v21
	v_cvt_pk_bf16_f32 v1, v1, s0
	ds_write_b16 v152, v1 offset:448
	ds_read_b128 v[2:5], v147 offset:32
	s_waitcnt lgkmcnt(0)
	v_mul_f32_e32 v1, v6, v2
	v_cvt_pk_bf16_f32 v1, v1, s0
	ds_write_b16 v152, v1 offset:1024
	v_mul_f32_e32 v1, v84, v2
	v_cvt_pk_bf16_f32 v1, v1, s0
	ds_write_b16 v152, v1 offset:1088
	v_mul_f32_e32 v1, v7, v3
	v_cvt_pk_bf16_f32 v1, v1, s0
	ds_write_b16 v152, v1 offset:1152
	v_mul_f32_e32 v1, v85, v3
	v_cvt_pk_bf16_f32 v1, v1, s0
	ds_write_b16 v152, v1 offset:1216
	v_mul_f32_e32 v1, v8, v4
	v_cvt_pk_bf16_f32 v1, v1, s0
	ds_write_b16 v152, v1 offset:1280
	v_mul_f32_e32 v1, v86, v4
	v_cvt_pk_bf16_f32 v1, v1, s0
	ds_write_b16 v152, v1 offset:1344
	v_mul_f32_e32 v1, v9, v5
	v_cvt_pk_bf16_f32 v1, v1, s0
	ds_write_b16 v152, v1 offset:1408
	v_mul_f32_e32 v1, v87, v5
	v_cvt_pk_bf16_f32 v1, v1, s0
	ds_write_b16 v152, v1 offset:1472
	ds_read_b128 v[2:5], v147 offset:64
	v_lshl_add_u64 v[6:7], v[140:141], 0, s[90:91]
	v_add_co_u32_e32 v8, vcc, s2, v6
	s_mov_b32 s2, 0x1d408000
	s_waitcnt lgkmcnt(0)
	v_mul_f32_e32 v1, v10, v2
	v_cvt_pk_bf16_f32 v1, v1, s0
	ds_write_b16 v152, v1 offset:2048
	v_mul_f32_e32 v1, v88, v2
	v_cvt_pk_bf16_f32 v1, v1, s0
	ds_write_b16 v152, v1 offset:2112
	v_mul_f32_e32 v1, v11, v3
	v_cvt_pk_bf16_f32 v1, v1, s0
	ds_write_b16 v152, v1 offset:2176
	v_mul_f32_e32 v1, v89, v3
	v_cvt_pk_bf16_f32 v1, v1, s0
	ds_write_b16 v152, v1 offset:2240
	v_mul_f32_e32 v1, v12, v4
	v_cvt_pk_bf16_f32 v1, v1, s0
	ds_write_b16 v152, v1 offset:2304
	v_mul_f32_e32 v1, v90, v4
	v_cvt_pk_bf16_f32 v1, v1, s0
	ds_write_b16 v152, v1 offset:2368
	v_mul_f32_e32 v1, v13, v5
	v_cvt_pk_bf16_f32 v1, v1, s0
	ds_write_b16 v152, v1 offset:2432
	v_mul_f32_e32 v1, v91, v5
	v_cvt_pk_bf16_f32 v1, v1, s0
	ds_write_b16 v152, v1 offset:2496
	ds_read_b128 v[2:5], v147 offset:96
	v_addc_co_u32_e32 v9, vcc, 0, v7, vcc
	s_add_u32 s90, s90, 0x20000
	s_addc_u32 s91, s91, 0
	s_waitcnt lgkmcnt(0)
	v_mul_f32_e32 v1, v14, v2
	v_cvt_pk_bf16_f32 v1, v1, s0
	ds_write_b16 v152, v1 offset:3072
	v_mul_f32_e32 v1, v92, v2
	v_cvt_pk_bf16_f32 v1, v1, s0
	ds_write_b16 v152, v1 offset:3136
	v_mul_f32_e32 v1, v15, v3
	v_cvt_pk_bf16_f32 v1, v1, s0
	ds_write_b16 v152, v1 offset:3200
	v_mul_f32_e32 v1, v93, v3
	v_cvt_pk_bf16_f32 v1, v1, s0
	ds_write_b16 v152, v1 offset:3264
	v_mul_f32_e32 v1, v16, v4
	v_cvt_pk_bf16_f32 v1, v1, s0
	ds_write_b16 v152, v1 offset:3328
	v_mul_f32_e32 v1, v94, v4
	v_cvt_pk_bf16_f32 v1, v1, s0
	ds_write_b16 v152, v1 offset:3392
	v_mul_f32_e32 v1, v17, v5
	v_cvt_pk_bf16_f32 v1, v1, s0
	ds_write_b16 v152, v1 offset:3456
	v_mul_f32_e32 v1, v95, v5
	v_cvt_pk_bf16_f32 v1, v1, s0
	ds_write_b16 v152, v1 offset:3520
	s_waitcnt lgkmcnt(0)
	v_add_u32_e32 v1, v148, v149
	ds_read_b128 v[2:5], v1
	s_add_i32 s36, s36, 1
	s_cmp_eq_u32 s90, 0x80000
	s_waitcnt lgkmcnt(0)
	global_store_dwordx4 v[8:9], v[2:5], off
	ds_read_b128 v[2:5], v153
	v_add_co_u32_e32 v8, vcc, s2, v6
	s_mov_b32 s2, 0x1d410000
	s_nop 0
	v_addc_co_u32_e32 v9, vcc, 0, v7, vcc
	s_waitcnt lgkmcnt(0)
	global_store_dwordx4 v[8:9], v[2:5], off
	ds_read_b128 v[2:5], v154
	v_add_co_u32_e32 v8, vcc, s2, v6
	s_mov_b32 s2, 0x1d418000
	s_nop 0
	v_addc_co_u32_e32 v9, vcc, 0, v7, vcc
	s_waitcnt lgkmcnt(0)
	global_store_dwordx4 v[8:9], v[2:5], off
	ds_read_b128 v[2:5], v155
	v_add_co_u32_e32 v6, vcc, s2, v6
	s_mov_b64 s[2:3], 0x28000
	s_nop 0
	v_addc_co_u32_e32 v7, vcc, 0, v7, vcc
	v_lshl_add_u64 v[138:139], v[138:139], 0, s[2:3]
	s_waitcnt lgkmcnt(0)
	global_store_dwordx4 v[6:7], v[2:5], off
	s_waitcnt vmcnt(4)
	s_cbranch_scc0 .Lfa_top
	s_branch .LBB0_475
